# v132 + nt on EpiRes residual x loads only (stores unchanged)
# speedup vs baseline: 1.0199x; 1.0040x over previous
.LBB0_519:
	s_min_i32 s25, s47, 0x80
	s_lshr_b32 s25, s25, 4
	s_mul_i32 s40, s25, 0x1800
	s_ashr_i32 s41, s40, 31
	s_lshl_b64 s[40:41], s[40:41], 2
	s_add_u32 s42, s18, s40
	s_addc_u32 s43, s19, s41
	s_cmpk_lt_i32 s47, 0x80
	v_lshl_add_u32 v146, s47, 18, v143
	v_add_u32_e32 v0, 0xfe000000, v146
	s_cselect_b64 vcc, -1, 0
	v_lshl_or_b32 v140, s46, 8, v144
	v_cndmask_b32_e32 v147, v0, v146, vcc
	s_and_b64 s[40:41], vcc, exec
	v_add_u32_e32 v0, v147, v140
	s_cselect_b32 s41, s15, s55
	s_cselect_b32 s40, s16, s54
	v_lshlrev_b64 v[152:153], 2, v[0:1]
	v_mov_b32_e32 v141, v1
	v_lshl_add_u64 v[146:147], s[40:41], 0, v[152:153]
	v_lshl_add_u64 v[138:139], v[140:141], 2, s[42:43]
	global_load_dwordx4 v[172:175], v[138:139], off
	global_load_dwordx4 v[176:179], v[138:139], off offset:64
	global_load_dwordx4 v[180:183], v[138:139], off offset:512
	global_load_dwordx4 v[184:187], v[138:139], off offset:576
	v_readlane_b32 s56, v254, 4
	v_readlane_b32 s70, v254, 18
	v_readlane_b32 s71, v254, 19
	s_cselect_b32 s43, s71, s55
	s_cselect_b32 s42, s70, s54
	v_lshl_add_u64 v[152:153], s[42:43], 0, v[152:153]
	v_readlane_b32 s57, v254, 5
	v_readlane_b32 s58, v254, 6
	v_readlane_b32 s59, v254, 7
	v_readlane_b32 s60, v254, 8
	v_readlane_b32 s61, v254, 9
	v_readlane_b32 s62, v254, 10
	v_readlane_b32 s63, v254, 11
	v_readlane_b32 s64, v254, 12
	v_readlane_b32 s65, v254, 13
	v_readlane_b32 s66, v254, 14
	v_readlane_b32 s67, v254, 15
	v_readlane_b32 s68, v254, 16
	v_readlane_b32 s69, v254, 17
	s_mov_b64 s[40:41], 0x10000
	s_mov_b64 s[42:43], 0x50000
	global_load_dwordx4 v[148:151], v[146:147], off nt
	global_load_dwordx4 v[168:171], v[146:147], off offset:64 nt
	global_load_dwordx4 v[188:191], v[146:147], off offset:512 nt
	global_load_dwordx4 v[192:195], v[146:147], off offset:576 nt
	v_lshl_add_u64 v[146:147], v[146:147], 0, s[40:41]
	global_load_dwordx4 v[196:199], v[146:147], off nt
	global_load_dwordx4 v[200:203], v[146:147], off offset:64 nt
	global_load_dwordx4 v[204:207], v[146:147], off offset:512 nt
	global_load_dwordx4 v[208:211], v[146:147], off offset:576 nt
	v_lshl_add_u64 v[146:147], v[146:147], 0, s[40:41]
	global_load_dwordx4 v[212:215], v[146:147], off nt
	global_load_dwordx4 v[224:227], v[146:147], off offset:64 nt
	global_load_dwordx4 v[234:237], v[146:147], off offset:512 nt
	global_load_dwordx4 v[238:241], v[146:147], off offset:576 nt
	s_waitcnt vmcnt(11)
	v_pk_fma_f32 v[128:129], v[128:129], v[174:175], v[150:151]
	v_pk_fma_f32 v[126:127], v[126:127], v[172:173], v[148:149]
	global_store_dwordx4 v[152:153], v[126:129], off
	v_lshl_add_u64 v[146:147], v[146:147], 0, s[40:41]
	global_load_dwordx4 v[148:151], v[146:147], off nt
	s_waitcnt vmcnt(12)
	v_pk_fma_f32 v[124:125], v[124:125], v[178:179], v[170:171]
	v_pk_fma_f32 v[122:123], v[122:123], v[176:177], v[168:169]
	global_store_dwordx4 v[152:153], v[122:125], off offset:64
	global_load_dwordx4 v[168:171], v[146:147], off offset:64 nt
	s_waitcnt vmcnt(13)
	v_pk_fma_f32 v[120:121], v[120:121], v[182:183], v[190:191]
	v_pk_fma_f32 v[118:119], v[118:119], v[180:181], v[188:189]
	global_store_dwordx4 v[152:153], v[118:121], off offset:512
	global_load_dwordx4 v[188:191], v[146:147], off offset:512 nt
	s_waitcnt vmcnt(14)
	v_pk_fma_f32 v[112:113], v[112:113], v[186:187], v[194:195]
	v_pk_fma_f32 v[110:111], v[110:111], v[184:185], v[192:193]
	global_store_dwordx4 v[152:153], v[110:113], off offset:576
	global_load_dwordx4 v[192:195], v[146:147], off offset:576 nt
	s_waitcnt vmcnt(15)
	v_pk_fma_f32 v[116:117], v[116:117], v[174:175], v[198:199]
	v_pk_fma_f32 v[114:115], v[114:115], v[172:173], v[196:197]
	v_lshl_add_u64 v[152:153], v[152:153], 0, s[40:41]
	global_store_dwordx4 v[152:153], v[114:117], off
	v_lshl_add_u64 v[146:147], v[146:147], 0, s[42:43]
	global_load_dwordx4 v[196:199], v[146:147], off nt
	s_waitcnt vmcnt(16)
	v_pk_fma_f32 v[108:109], v[108:109], v[178:179], v[202:203]
	v_pk_fma_f32 v[106:107], v[106:107], v[176:177], v[200:201]
	global_store_dwordx4 v[152:153], v[106:109], off offset:64
	global_load_dwordx4 v[200:203], v[146:147], off offset:64 nt
	s_waitcnt vmcnt(17)
	v_pk_fma_f32 v[104:105], v[104:105], v[182:183], v[206:207]
	v_pk_fma_f32 v[102:103], v[102:103], v[180:181], v[204:205]
	global_store_dwordx4 v[152:153], v[102:105], off offset:512
	global_load_dwordx4 v[204:207], v[146:147], off offset:512 nt
	s_waitcnt vmcnt(18)
	v_pk_fma_f32 v[96:97], v[96:97], v[186:187], v[210:211]
	v_pk_fma_f32 v[94:95], v[94:95], v[184:185], v[208:209]
	global_store_dwordx4 v[152:153], v[94:97], off offset:576
	global_load_dwordx4 v[208:211], v[146:147], off offset:576 nt
	s_waitcnt vmcnt(19)
	v_pk_fma_f32 v[100:101], v[100:101], v[174:175], v[214:215]
	v_pk_fma_f32 v[98:99], v[98:99], v[172:173], v[212:213]
	v_lshl_add_u64 v[152:153], v[152:153], 0, s[40:41]
	global_store_dwordx4 v[152:153], v[98:101], off
	v_lshl_add_u64 v[146:147], v[146:147], 0, s[40:41]
	global_load_dwordx4 v[212:215], v[146:147], off nt
	s_waitcnt vmcnt(20)
	v_pk_fma_f32 v[92:93], v[92:93], v[178:179], v[226:227]
	v_pk_fma_f32 v[90:91], v[90:91], v[176:177], v[224:225]
	global_store_dwordx4 v[152:153], v[90:93], off offset:64
	global_load_dwordx4 v[224:227], v[146:147], off offset:64 nt
	s_waitcnt vmcnt(21)
	v_pk_fma_f32 v[88:89], v[88:89], v[182:183], v[236:237]
	v_pk_fma_f32 v[86:87], v[86:87], v[180:181], v[234:235]
	global_store_dwordx4 v[152:153], v[86:89], off offset:512
	global_load_dwordx4 v[234:237], v[146:147], off offset:512 nt
	s_waitcnt vmcnt(22)
	v_pk_fma_f32 v[80:81], v[80:81], v[186:187], v[240:241]
	v_pk_fma_f32 v[78:79], v[78:79], v[184:185], v[238:239]
	global_store_dwordx4 v[152:153], v[78:81], off offset:576
	global_load_dwordx4 v[238:241], v[146:147], off offset:576 nt
	s_waitcnt vmcnt(22)
	v_pk_fma_f32 v[84:85], v[84:85], v[174:175], v[150:151]
	v_pk_fma_f32 v[82:83], v[82:83], v[172:173], v[148:149]
	v_lshl_add_u64 v[152:153], v[152:153], 0, s[40:41]
	global_store_dwordx4 v[152:153], v[82:85], off
	v_lshl_add_u64 v[146:147], v[146:147], 0, s[40:41]
	global_load_dwordx4 v[148:151], v[146:147], off nt
	s_waitcnt vmcnt(22)
	v_pk_fma_f32 v[76:77], v[76:77], v[178:179], v[170:171]
	v_pk_fma_f32 v[74:75], v[74:75], v[176:177], v[168:169]
	global_store_dwordx4 v[152:153], v[74:77], off offset:64
	global_load_dwordx4 v[168:171], v[146:147], off offset:64 nt
	s_waitcnt vmcnt(22)
	v_pk_fma_f32 v[72:73], v[72:73], v[182:183], v[190:191]
	v_pk_fma_f32 v[70:71], v[70:71], v[180:181], v[188:189]
	global_store_dwordx4 v[152:153], v[70:73], off offset:512
	global_load_dwordx4 v[188:191], v[146:147], off offset:512 nt
	s_waitcnt vmcnt(22)
	v_pk_fma_f32 v[68:69], v[68:69], v[186:187], v[194:195]
	v_pk_fma_f32 v[66:67], v[66:67], v[184:185], v[192:193]
	global_store_dwordx4 v[152:153], v[66:69], off offset:576
	global_load_dwordx4 v[192:195], v[146:147], off offset:576 nt
	s_waitcnt vmcnt(22)
	v_pk_fma_f32 v[64:65], v[64:65], v[174:175], v[198:199]
	v_pk_fma_f32 v[62:63], v[62:63], v[172:173], v[196:197]
	v_lshl_add_u64 v[152:153], v[152:153], 0, s[42:43]
	global_store_dwordx4 v[152:153], v[62:65], off
	v_lshl_add_u64 v[146:147], v[146:147], 0, s[40:41]
	global_load_dwordx4 v[196:199], v[146:147], off nt
	s_waitcnt vmcnt(22)
	v_pk_fma_f32 v[60:61], v[60:61], v[178:179], v[202:203]
	v_pk_fma_f32 v[58:59], v[58:59], v[176:177], v[200:201]
	global_store_dwordx4 v[152:153], v[58:61], off offset:64
	global_load_dwordx4 v[200:203], v[146:147], off offset:64 nt
	s_waitcnt vmcnt(22)
	v_pk_fma_f32 v[56:57], v[56:57], v[182:183], v[206:207]
	v_pk_fma_f32 v[54:55], v[54:55], v[180:181], v[204:205]
	global_store_dwordx4 v[152:153], v[54:57], off offset:512
	global_load_dwordx4 v[204:207], v[146:147], off offset:512 nt
	s_waitcnt vmcnt(22)
	v_pk_fma_f32 v[48:49], v[48:49], v[186:187], v[210:211]
	v_pk_fma_f32 v[46:47], v[46:47], v[184:185], v[208:209]
	global_store_dwordx4 v[152:153], v[46:49], off offset:576
	global_load_dwordx4 v[208:211], v[146:147], off offset:576 nt
	s_waitcnt vmcnt(22)
	v_pk_fma_f32 v[52:53], v[52:53], v[174:175], v[214:215]
	v_pk_fma_f32 v[50:51], v[50:51], v[172:173], v[212:213]
	v_lshl_add_u64 v[152:153], v[152:153], 0, s[40:41]
	global_store_dwordx4 v[152:153], v[50:53], off
	s_waitcnt vmcnt(21)
	v_pk_fma_f32 v[44:45], v[44:45], v[178:179], v[226:227]
	v_pk_fma_f32 v[42:43], v[42:43], v[176:177], v[224:225]
	global_store_dwordx4 v[152:153], v[42:45], off offset:64
	s_waitcnt vmcnt(20)
	v_pk_fma_f32 v[40:41], v[40:41], v[182:183], v[236:237]
	v_pk_fma_f32 v[38:39], v[38:39], v[180:181], v[234:235]
	global_store_dwordx4 v[152:153], v[38:41], off offset:512
	s_waitcnt vmcnt(19)
	v_pk_fma_f32 v[32:33], v[32:33], v[186:187], v[240:241]
	v_pk_fma_f32 v[30:31], v[30:31], v[184:185], v[238:239]
	global_store_dwordx4 v[152:153], v[30:33], off offset:576
	s_waitcnt vmcnt(18)
	v_pk_fma_f32 v[36:37], v[36:37], v[174:175], v[150:151]
	v_pk_fma_f32 v[34:35], v[34:35], v[172:173], v[148:149]
	v_lshl_add_u64 v[152:153], v[152:153], 0, s[40:41]
	global_store_dwordx4 v[152:153], v[34:37], off
	s_waitcnt vmcnt(17)
	v_pk_fma_f32 v[28:29], v[28:29], v[178:179], v[170:171]
	v_pk_fma_f32 v[26:27], v[26:27], v[176:177], v[168:169]
	global_store_dwordx4 v[152:153], v[26:29], off offset:64
	s_waitcnt vmcnt(16)
	v_pk_fma_f32 v[24:25], v[24:25], v[182:183], v[190:191]
	v_pk_fma_f32 v[22:23], v[22:23], v[180:181], v[188:189]
	global_store_dwordx4 v[152:153], v[22:25], off offset:512
	s_waitcnt vmcnt(15)
	v_pk_fma_f32 v[16:17], v[16:17], v[186:187], v[194:195]
	v_pk_fma_f32 v[14:15], v[14:15], v[184:185], v[192:193]
	global_store_dwordx4 v[152:153], v[14:17], off offset:576
	s_waitcnt vmcnt(14)
	v_pk_fma_f32 v[20:21], v[20:21], v[174:175], v[198:199]
	v_pk_fma_f32 v[18:19], v[18:19], v[172:173], v[196:197]
	v_lshl_add_u64 v[152:153], v[152:153], 0, s[40:41]
	global_store_dwordx4 v[152:153], v[18:21], off
	s_waitcnt vmcnt(13)
	v_pk_fma_f32 v[12:13], v[12:13], v[178:179], v[202:203]
	v_pk_fma_f32 v[10:11], v[10:11], v[176:177], v[200:201]
	global_store_dwordx4 v[152:153], v[10:13], off offset:64
	s_waitcnt vmcnt(12)
	v_pk_fma_f32 v[8:9], v[8:9], v[182:183], v[206:207]
	v_pk_fma_f32 v[6:7], v[6:7], v[180:181], v[204:205]
	global_store_dwordx4 v[152:153], v[6:9], off offset:512
	s_waitcnt vmcnt(11)
	v_pk_fma_f32 v[4:5], v[4:5], v[186:187], v[210:211]
	v_pk_fma_f32 v[2:3], v[2:3], v[184:185], v[208:209]
	global_store_dwordx4 v[152:153], v[2:5], off offset:576
	s_andn2_b64 vcc, exec, s[38:39]
	s_mov_b64 s[38:39], -1
	s_cbranch_vccnz .LBB0_508
	s_andn2_b64 vcc, exec, s[2:3]
	s_cbranch_vccnz .LBB0_507
	s_barrier
	s_branch .LBB0_507
